# chunk-MLP U gate tile loads widened to dwordx4 with permlane16 swap (on top of the widened stores)
# speedup vs baseline: 1.0003x; 1.0003x over previous
.Lcma_pf0:
	global_load_dwordx4 v[100:103], v200, s[46:47]
	global_load_dwordx4 v[116:119], v204, s[48:49]
	global_load_dwordx4 v[104:107], v201, s[46:47]
	global_load_dwordx4 v[120:123], v205, s[48:49]
	global_load_dwordx4 v[108:111], v202, s[46:47]
	global_load_dwordx4 v[124:127], v206, s[48:49]
	global_load_dwordx4 v[112:115], v203, s[46:47]
	global_load_dwordx4 v[128:131], v207, s[48:49]
	global_load_dwordx4 v[164:167], v209, s[14:15]
	global_load_dwordx4 v[168:171], v209, s[16:17]
	global_load_dwordx4 v[172:175], v209, s[16:17] offset:16
	global_load_dwordx4 v[176:179], v209, s[14:15] offset:16
	global_load_dword v236, v210, s[10:11]
	global_load_dwordx4 v[220:223], v218, s[6:7]
	global_load_dwordx4 v[224:227], v218, s[6:7] offset:64
	global_load_dwordx4 v[228:231], v218, s[6:7] offset:128
	global_load_dwordx4 v[232:235], v218, s[6:7] offset:192
	s_waitcnt vmcnt(0)
	v_readfirstlane_b32 s0, v195
	s_nop 1
	s_cmp_lt_u32 s0, 0x80
	s_cbranch_scc0 .Lcma_nostat
	v_pk_add_f32 v[56:57], v[132:133], v[134:135]
	v_pk_add_f32 v[60:61], v[136:137], v[138:139]
	v_pk_add_f32 v[56:57], v[56:57], 0 op_sel_hi:[1,0]
	v_pk_add_f32 v[58:59], v[140:141], v[142:143]
	v_pk_add_f32 v[56:57], v[56:57], v[60:61]
	v_pk_add_f32 v[60:61], v[144:145], v[146:147]
	v_pk_add_f32 v[56:57], v[56:57], v[58:59]
	v_pk_add_f32 v[58:59], v[148:149], v[150:151]
	v_pk_add_f32 v[56:57], v[56:57], v[60:61]
	v_pk_add_f32 v[60:61], v[152:153], v[154:155]
	v_pk_add_f32 v[56:57], v[56:57], v[58:59]
	v_pk_add_f32 v[58:59], v[156:157], v[158:159]
	v_pk_add_f32 v[56:57], v[56:57], v[60:61]
	v_pk_add_f32 v[60:61], v[160:161], v[162:163]
	v_pk_add_f32 v[56:57], v[56:57], v[58:59]
	s_nop 0
	v_pk_add_f32 v[56:57], v[56:57], v[60:61]
	s_nop 0
	v_pk_mul_f32 v[56:57], v[56:57], s[4:5] op_sel_hi:[1,0]
	s_nop 0
	v_fma_f32 v58, -v56, v56, v57
	v_max_f32_e32 v58, 0, v58
	v_add_f32_e32 v58, 0x358637bd, v58
	v_rsq_f32_e32 v57, v58
	s_nop 1
	ds_write_b64 v215, v[56:57]

.Lcma_copy:
	s_mov_b64 s[12:13], s[6:7]
	v_mov_b32_e32 v0, v100
	v_mov_b32_e32 v1, v101
	v_mov_b32_e32 v2, v102
	v_mov_b32_e32 v3, v103
	v_mov_b32_e32 v4, v104
	v_mov_b32_e32 v5, v105
	v_mov_b32_e32 v6, v106
	v_mov_b32_e32 v7, v107
	v_mov_b32_e32 v8, v108
	v_mov_b32_e32 v9, v109
	v_mov_b32_e32 v10, v110
	v_mov_b32_e32 v11, v111
	v_mov_b32_e32 v12, v112
	v_mov_b32_e32 v13, v113
	v_mov_b32_e32 v14, v114
	v_mov_b32_e32 v15, v115
	v_mov_b32_e32 v16, v116
	v_mov_b32_e32 v17, v117
	v_mov_b32_e32 v18, v118
	v_mov_b32_e32 v19, v119
	v_mov_b32_e32 v20, v120
	v_mov_b32_e32 v21, v121
	v_mov_b32_e32 v22, v122
	v_mov_b32_e32 v23, v123
	v_mov_b32_e32 v24, v124
	v_mov_b32_e32 v25, v125
	v_mov_b32_e32 v26, v126
	v_mov_b32_e32 v27, v127
	v_mov_b32_e32 v28, v128
	v_mov_b32_e32 v29, v129
	v_mov_b32_e32 v30, v130
	v_mov_b32_e32 v31, v131
	v_mov_b32_e32 v38, v164
	v_mov_b32_e32 v39, v165
	v_mov_b32_e32 v40, v166
	v_mov_b32_e32 v41, v167
	v_mov_b32_e32 v42, v168
	v_mov_b32_e32 v43, v169
	v_mov_b32_e32 v44, v170
	v_mov_b32_e32 v45, v171
	v_mov_b32_e32 v46, v172
	v_mov_b32_e32 v47, v173
	v_mov_b32_e32 v48, v174
	v_mov_b32_e32 v49, v175
	v_mov_b32_e32 v50, v176
	v_mov_b32_e32 v51, v177
	v_mov_b32_e32 v52, v178
	v_mov_b32_e32 v53, v179
	v_mov_b32_e32 v70, v220
	v_mov_b32_e32 v71, v221
	v_mov_b32_e32 v72, v222
	v_mov_b32_e32 v73, v223
	v_mov_b32_e32 v74, v224
	v_mov_b32_e32 v75, v225
	v_mov_b32_e32 v76, v226
	v_mov_b32_e32 v77, v227
	v_mov_b32_e32 v78, v228
	v_mov_b32_e32 v79, v229
	v_mov_b32_e32 v80, v230
	v_mov_b32_e32 v81, v231
	v_mov_b32_e32 v82, v232
	v_mov_b32_e32 v83, v233
	v_mov_b32_e32 v84, v234
	v_mov_b32_e32 v85, v235
	v_mov_b32_e32 v86, v236
	s_nop 1
	v_permlane16_swap_b32 v70, v72
	v_permlane16_swap_b32 v71, v73
	v_permlane16_swap_b32 v74, v76
	v_permlane16_swap_b32 v75, v77
	v_permlane16_swap_b32 v78, v80
	v_permlane16_swap_b32 v79, v81
	v_permlane16_swap_b32 v82, v84
	v_permlane16_swap_b32 v83, v85
	s_cmp_gt_u32 s3, 1
	s_cbranch_scc0 .Lcma_nopf
	s_add_i32 s0, s5, 1
	s_and_b32 s1, s0, 7
	s_lshr_b32 s0, s0, 3
	s_lshl_b32 s0, s0, 7
	s_lshl_b32 s10, s1, 8
	s_lshl_b32 s11, s0, 11
	s_add_u32 s11, s11, s10
	s_add_u32 s46, s42, s11
	s_addc_u32 s47, s43, 0
	s_add_u32 s6, s96, s11
	s_addc_u32 s7, s97, 0
	s_lshl_b32 s10, s1, 15
	s_add_u32 s48, s8, s10
	s_addc_u32 s49, s9, 0
	s_lshl_b32 s10, s0, 7
	s_add_u32 s50, s44, s10
	s_addc_u32 s51, s45, 0
	s_lshl_b32 s10, s1, 9
	s_add_u32 s14, s36, s10
	s_addc_u32 s15, s37, 0
	s_add_u32 s16, s38, s10
	s_addc_u32 s17, s39, 0
	s_add_u32 s10, s40, s10
	s_addc_u32 s11, s41, 0
	global_load_dwordx4 v[100:103], v200, s[46:47]
	global_load_dwordx4 v[116:119], v204, s[48:49]
	global_load_dwordx4 v[104:107], v201, s[46:47]
	global_load_dwordx4 v[120:123], v205, s[48:49]
	global_load_dwordx4 v[108:111], v202, s[46:47]
	global_load_dwordx4 v[124:127], v206, s[48:49]
	global_load_dwordx4 v[112:115], v203, s[46:47]
	global_load_dwordx4 v[128:131], v207, s[48:49]
	global_load_dwordx4 v[164:167], v209, s[14:15]
	global_load_dwordx4 v[168:171], v209, s[16:17]
	global_load_dwordx4 v[172:175], v209, s[16:17] offset:16
	global_load_dwordx4 v[176:179], v209, s[14:15] offset:16
	global_load_dword v236, v210, s[10:11]
	global_load_dwordx4 v[220:223], v218, s[6:7]
	global_load_dwordx4 v[224:227], v218, s[6:7] offset:64
	global_load_dwordx4 v[228:231], v218, s[6:7] offset:128
	global_load_dwordx4 v[232:235], v218, s[6:7] offset:192
